# ph14 NA units: unit-id bits 3 and 8 swapped so co-resident blocks work on adjacent row pairs of one (batch, head)
# speedup vs baseline: 1.0031x; 1.0031x over previous
.LBB0_1778:
	s_and_b64 vcc, exec, s[4:5]
	s_cbranch_vccz .LBB0_1759
	s_lshr_b32 s4, s86, 3
	s_lshr_b32 s5, s86, 8
	s_xor_b32 s4, s4, s5
	s_and_b32 s4, s4, 1
	s_mulk_i32 s4, 0x108
	s_xor_b32 s80, s86, s4
	s_lshl_b32 s4, s80, 3
	s_and_b32 s4, s4, 56
	s_ashr_i32 s5, s80, 7
	s_add_i32 s4, s4, s5
	s_lshr_b32 s5, s80, 2
	s_and_b32 s81, s5, 30
	s_ashr_i32 s80, s4, 4
	v_or_b32_e32 v137, s81, v114
	s_lshl_b32 s5, s80, 11
	v_lshlrev_b32_e32 v2, 6, v137
	v_add3_u32 v2, v115, v2, s5
	v_ashrrev_i32_e32 v3, 31, v2
	s_and_b32 s4, s4, 15
	v_lshlrev_b64 v[4:5], 11, v[2:3]
	v_lshl_add_u64 v[4:5], s[12:13], 0, v[4:5]
	s_lshl_b32 s24, s4, 7
	v_lshl_add_u64 v[4:5], v[4:5], 0, s[24:25]
	v_mov_b32_e32 v93, v69
	v_lshl_add_u64 v[4:5], v[4:5], 0, v[92:93]
	global_load_dwordx4 v[50:53], v[4:5], off
	global_load_dwordx4 v[54:57], v[4:5], off offset:32
	global_load_dwordx4 v[58:61], v[4:5], off offset:64
	global_load_dwordx4 v[62:65], v[4:5], off offset:96
	s_lshl_b32 s24, s4, 6
	s_mulk_i32 s4, 0x1d1
	v_sub_u32_e64 v4, s81, 3 clamp
	v_lshlrev_b64 v[94:95], 10, v[2:3]
	v_add_u32_e32 v2, s4, v123
	v_mov_b32_e32 v3, v69
	v_readfirstlane_b32 s82, v4
	v_lshl_add_u64 v[2:3], v[2:3], 2, s[26:27]
	s_mov_b64 s[4:5], 0
	v_mov_b32_e32 v4, v124
	v_mov_b32_e32 v5, v122
	v_mov_b32_e32 v6, v121
	s_barrier
	s_branch .LBB0_1781
